# final RMSNorm fast path: 4 tokens per wave with batched loads
# speedup vs baseline: 1.0011x; 1.0011x over previous
.LBB0_2318:
	v_mov_b32_e32 v7, 0
	ds_read_b64 v[4:5], v7 offset:63744
	ds_read_b64 v[2:3], v7 offset:63760
	v_ashrrev_i32_e32 v0, 6, v231
	s_movk_i32 s0, 0x2000
	v_lshl_add_u32 v0, s76, 2, v0
	v_cmp_gt_i32_e32 vcc, s0, v0
	s_and_saveexec_b64 s[0:1], vcc
	s_cbranch_execz .LBB0_2321
	v_lshlrev_b32_e32 v1, 4, v231
	v_and_b32_e32 v6, 0x3f0, v1
	v_and_b32_e32 v1, 64, v244
	v_add_u32_e32 v1, 64, v1
	v_xor_b32_e32 v8, 32, v244
	v_cmp_lt_i32_e32 vcc, v8, v1
	v_xor_b32_e32 v9, 16, v244
	v_xor_b32_e32 v10, 8, v244
	v_cndmask_b32_e32 v8, v244, v8, vcc
	v_cmp_lt_i32_e32 vcc, v9, v1
	v_xor_b32_e32 v11, 4, v244
	ds_read_b64 v[14:15], v7 offset:63752
	v_cndmask_b32_e32 v9, v244, v9, vcc
	v_cmp_lt_i32_e32 vcc, v10, v1
	v_xor_b32_e32 v12, 2, v244
	v_xor_b32_e32 v13, 1, v244
	v_cndmask_b32_e32 v10, v244, v10, vcc
	v_cmp_lt_i32_e32 vcc, v11, v1
	s_waitcnt lgkmcnt(0)
	v_lshl_add_u64 v[2:3], v[2:3], 0, v[6:7]
	s_mov_b64 s[0:1], 0x2ad4000
	v_cndmask_b32_e32 v11, v244, v11, vcc
	v_cmp_lt_i32_e32 vcc, v12, v1
	v_lshl_add_u64 v[2:3], v[2:3], 0, s[0:1]
	v_lshlrev_b32_e32 v8, 2, v8
	v_cndmask_b32_e32 v12, v244, v12, vcc
	v_cmp_lt_i32_e32 vcc, v13, v1
	v_lshlrev_b32_e32 v9, 2, v9
	v_lshlrev_b32_e32 v10, 2, v10
	v_cndmask_b32_e32 v1, v244, v13, vcc
	v_lshlrev_b32_e32 v11, 2, v11
	v_lshlrev_b32_e32 v12, 2, v12
	v_lshlrev_b32_e32 v13, 2, v1
	v_lshl_add_u64 v[4:5], v[4:5], 0, v[6:7]
	v_lshl_add_u64 v[6:7], v[14:15], 0, v[6:7]
	s_mov_b64 s[0:1], 0
	v_mov_b32_e32 v14, 0x358637bd
	s_mov_b32 s2, 0x800000
	s_movk_i32 s3, 0x1fff
	s_cmp_eq_u32 s77, 0x800
	s_cbranch_scc0 .LBB0_2320
	v_readfirstlane_b32 s4, v0
	s_lshl_b32 s6, s4, 12
	s_mov_b32 s7, 0
	v_lshl_add_u64 v[60:61], v[2:3], 0, s[6:7]
	global_load_dwordx4 v[64:67], v[60:61], off
	global_load_dwordx4 v[68:71], v[60:61], off offset:1024
	global_load_dwordx4 v[72:75], v[60:61], off offset:2048
	global_load_dwordx4 v[76:79], v[60:61], off offset:3072
	s_add_u32 s6, s6, 0x800000
	v_lshl_add_u64 v[60:61], v[2:3], 0, s[6:7]
	global_load_dwordx4 v[80:83], v[60:61], off
	global_load_dwordx4 v[84:87], v[60:61], off offset:1024
	global_load_dwordx4 v[88:91], v[60:61], off offset:2048
	global_load_dwordx4 v[92:95], v[60:61], off offset:3072
	s_add_u32 s6, s6, 0x800000
	v_lshl_add_u64 v[60:61], v[2:3], 0, s[6:7]
	global_load_dwordx4 v[96:99], v[60:61], off
	global_load_dwordx4 v[100:103], v[60:61], off offset:1024
	global_load_dwordx4 v[104:107], v[60:61], off offset:2048
	global_load_dwordx4 v[108:111], v[60:61], off offset:3072
	s_add_u32 s6, s6, 0x800000
	v_lshl_add_u64 v[60:61], v[2:3], 0, s[6:7]
	global_load_dwordx4 v[112:115], v[60:61], off
	global_load_dwordx4 v[116:119], v[60:61], off offset:1024
	global_load_dwordx4 v[120:123], v[60:61], off offset:2048
	global_load_dwordx4 v[124:127], v[60:61], off offset:3072
	global_load_dwordx4 v[128:131], v[4:5], off
	global_load_dwordx4 v[132:135], v[4:5], off offset:1024
	global_load_dwordx4 v[136:139], v[4:5], off offset:2048
	global_load_dwordx4 v[140:143], v[4:5], off offset:3072
	s_waitcnt vmcnt(4)
	v_mul_f32_e32 v212, v65, v65
	v_fmac_f32_e32 v212, v64, v64
	v_fmac_f32_e32 v212, v66, v66
	v_fmac_f32_e32 v212, v67, v67
	v_mul_f32_e32 v213, v69, v69
	v_fmac_f32_e32 v213, v68, v68
	v_fmac_f32_e32 v213, v70, v70
	v_fmac_f32_e32 v213, v71, v71
	v_mul_f32_e32 v214, v73, v73
	v_fmac_f32_e32 v214, v72, v72
	v_fmac_f32_e32 v214, v74, v74
	v_fmac_f32_e32 v214, v75, v75
	v_mul_f32_e32 v215, v77, v77
	v_fmac_f32_e32 v215, v76, v76
	v_fmac_f32_e32 v215, v78, v78
	v_fmac_f32_e32 v215, v79, v79
	v_add_f32_e32 v208, v212, v213
	v_add_f32_e32 v208, v208, v214
	v_add_f32_e32 v208, v208, v215
	v_mul_f32_e32 v212, v81, v81
	v_fmac_f32_e32 v212, v80, v80
	v_fmac_f32_e32 v212, v82, v82
	v_fmac_f32_e32 v212, v83, v83
	v_mul_f32_e32 v213, v85, v85
	v_fmac_f32_e32 v213, v84, v84
	v_fmac_f32_e32 v213, v86, v86
	v_fmac_f32_e32 v213, v87, v87
	v_mul_f32_e32 v214, v89, v89
	v_fmac_f32_e32 v214, v88, v88
	v_fmac_f32_e32 v214, v90, v90
	v_fmac_f32_e32 v214, v91, v91
	v_mul_f32_e32 v215, v93, v93
	v_fmac_f32_e32 v215, v92, v92
	v_fmac_f32_e32 v215, v94, v94
	v_fmac_f32_e32 v215, v95, v95
	v_add_f32_e32 v209, v212, v213
	v_add_f32_e32 v209, v209, v214
	v_add_f32_e32 v209, v209, v215
	v_mul_f32_e32 v212, v97, v97
	v_fmac_f32_e32 v212, v96, v96
	v_fmac_f32_e32 v212, v98, v98
	v_fmac_f32_e32 v212, v99, v99
	v_mul_f32_e32 v213, v101, v101
	v_fmac_f32_e32 v213, v100, v100
	v_fmac_f32_e32 v213, v102, v102
	v_fmac_f32_e32 v213, v103, v103
	v_mul_f32_e32 v214, v105, v105
	v_fmac_f32_e32 v214, v104, v104
	v_fmac_f32_e32 v214, v106, v106
	v_fmac_f32_e32 v214, v107, v107
	v_mul_f32_e32 v215, v109, v109
	v_fmac_f32_e32 v215, v108, v108
	v_fmac_f32_e32 v215, v110, v110
	v_fmac_f32_e32 v215, v111, v111
	v_add_f32_e32 v210, v212, v213
	v_add_f32_e32 v210, v210, v214
	v_add_f32_e32 v210, v210, v215
	v_mul_f32_e32 v212, v113, v113
	v_fmac_f32_e32 v212, v112, v112
	v_fmac_f32_e32 v212, v114, v114
	v_fmac_f32_e32 v212, v115, v115
	v_mul_f32_e32 v213, v117, v117
	v_fmac_f32_e32 v213, v116, v116
	v_fmac_f32_e32 v213, v118, v118
	v_fmac_f32_e32 v213, v119, v119
	v_mul_f32_e32 v214, v121, v121
	v_fmac_f32_e32 v214, v120, v120
	v_fmac_f32_e32 v214, v122, v122
	v_fmac_f32_e32 v214, v123, v123
	v_mul_f32_e32 v215, v125, v125
	v_fmac_f32_e32 v215, v124, v124
	v_fmac_f32_e32 v215, v126, v126
	v_fmac_f32_e32 v215, v127, v127
	v_add_f32_e32 v211, v212, v213
	v_add_f32_e32 v211, v211, v214
	v_add_f32_e32 v211, v211, v215
	ds_bpermute_b32 v212, v8, v208
	ds_bpermute_b32 v213, v8, v209
	ds_bpermute_b32 v214, v8, v210
	ds_bpermute_b32 v215, v8, v211
	s_waitcnt lgkmcnt(0)
	v_add_f32_e32 v208, v208, v212
	v_add_f32_e32 v209, v209, v213
	v_add_f32_e32 v210, v210, v214
	v_add_f32_e32 v211, v211, v215
	ds_bpermute_b32 v212, v9, v208
	ds_bpermute_b32 v213, v9, v209
	ds_bpermute_b32 v214, v9, v210
	ds_bpermute_b32 v215, v9, v211
	s_waitcnt lgkmcnt(0)
	v_add_f32_e32 v208, v208, v212
	v_add_f32_e32 v209, v209, v213
	v_add_f32_e32 v210, v210, v214
	v_add_f32_e32 v211, v211, v215
	ds_bpermute_b32 v212, v10, v208
	ds_bpermute_b32 v213, v10, v209
	ds_bpermute_b32 v214, v10, v210
	ds_bpermute_b32 v215, v10, v211
	s_waitcnt lgkmcnt(0)
	v_add_f32_e32 v208, v208, v212
	v_add_f32_e32 v209, v209, v213
	v_add_f32_e32 v210, v210, v214
	v_add_f32_e32 v211, v211, v215
	ds_bpermute_b32 v212, v11, v208
	ds_bpermute_b32 v213, v11, v209
	ds_bpermute_b32 v214, v11, v210
	ds_bpermute_b32 v215, v11, v211
	s_waitcnt lgkmcnt(0)
	v_add_f32_e32 v208, v208, v212
	v_add_f32_e32 v209, v209, v213
	v_add_f32_e32 v210, v210, v214
	v_add_f32_e32 v211, v211, v215
	ds_bpermute_b32 v212, v12, v208
	ds_bpermute_b32 v213, v12, v209
	ds_bpermute_b32 v214, v12, v210
	ds_bpermute_b32 v215, v12, v211
	s_waitcnt lgkmcnt(0)
	v_add_f32_e32 v208, v208, v212
	v_add_f32_e32 v209, v209, v213
	v_add_f32_e32 v210, v210, v214
	v_add_f32_e32 v211, v211, v215
	ds_bpermute_b32 v212, v13, v208
	ds_bpermute_b32 v213, v13, v209
	ds_bpermute_b32 v214, v13, v210
	ds_bpermute_b32 v215, v13, v211
	s_waitcnt lgkmcnt(0)
	v_add_f32_e32 v208, v208, v212
	v_add_f32_e32 v209, v209, v213
	v_add_f32_e32 v210, v210, v214
	v_add_f32_e32 v211, v211, v215
	v_fmamk_f32 v208, v208, 0x3a800000, v14
	v_mul_f32_e32 v212, 0x4b800000, v208
	v_cmp_gt_f32_e32 vcc, s2, v208
	s_nop 1
	v_cndmask_b32_e32 v208, v208, v212, vcc
	v_rsq_f32_e32 v208, v208
	s_nop 0
	v_mul_f32_e32 v212, 0x45800000, v208
	v_cndmask_b32_e32 v208, v208, v212, vcc
	v_fmamk_f32 v209, v209, 0x3a800000, v14
	v_mul_f32_e32 v212, 0x4b800000, v209
	v_cmp_gt_f32_e32 vcc, s2, v209
	s_nop 1
	v_cndmask_b32_e32 v209, v209, v212, vcc
	v_rsq_f32_e32 v209, v209
	s_nop 0
	v_mul_f32_e32 v212, 0x45800000, v209
	v_cndmask_b32_e32 v209, v209, v212, vcc
	v_fmamk_f32 v210, v210, 0x3a800000, v14
	v_mul_f32_e32 v212, 0x4b800000, v210
	v_cmp_gt_f32_e32 vcc, s2, v210
	s_nop 1
	v_cndmask_b32_e32 v210, v210, v212, vcc
	v_rsq_f32_e32 v210, v210
	s_nop 0
	v_mul_f32_e32 v212, 0x45800000, v210
	v_cndmask_b32_e32 v210, v210, v212, vcc
	v_fmamk_f32 v211, v211, 0x3a800000, v14
	v_mul_f32_e32 v212, 0x4b800000, v211
	v_cmp_gt_f32_e32 vcc, s2, v211
	s_nop 1
	v_cndmask_b32_e32 v211, v211, v212, vcc
	v_rsq_f32_e32 v211, v211
	s_nop 0
	v_mul_f32_e32 v212, 0x45800000, v211
	v_cndmask_b32_e32 v211, v211, v212, vcc
	s_waitcnt vmcnt(0)
	s_lshl_b32 s6, s4, 12
	v_lshl_add_u64 v[62:63], v[6:7], 0, s[6:7]
	v_mul_f32_e32 v64, v64, v208
	v_mul_f32_e32 v64, v128, v64
	v_mul_f32_e32 v65, v65, v208
	v_mul_f32_e32 v65, v129, v65
	v_mul_f32_e32 v66, v66, v208
	v_mul_f32_e32 v66, v130, v66
	v_mul_f32_e32 v67, v67, v208
	v_mul_f32_e32 v67, v131, v67
	global_store_dwordx4 v[62:63], v[64:67], off
	v_mul_f32_e32 v68, v68, v208
	v_mul_f32_e32 v68, v132, v68
	v_mul_f32_e32 v69, v69, v208
	v_mul_f32_e32 v69, v133, v69
	v_mul_f32_e32 v70, v70, v208
	v_mul_f32_e32 v70, v134, v70
	v_mul_f32_e32 v71, v71, v208
	v_mul_f32_e32 v71, v135, v71
	global_store_dwordx4 v[62:63], v[68:71], off offset:1024
	v_mul_f32_e32 v72, v72, v208
	v_mul_f32_e32 v72, v136, v72
	v_mul_f32_e32 v73, v73, v208
	v_mul_f32_e32 v73, v137, v73
	v_mul_f32_e32 v74, v74, v208
	v_mul_f32_e32 v74, v138, v74
	v_mul_f32_e32 v75, v75, v208
	v_mul_f32_e32 v75, v139, v75
	global_store_dwordx4 v[62:63], v[72:75], off offset:2048
	v_mul_f32_e32 v76, v76, v208
	v_mul_f32_e32 v76, v140, v76
	v_mul_f32_e32 v77, v77, v208
	v_mul_f32_e32 v77, v141, v77
	v_mul_f32_e32 v78, v78, v208
	v_mul_f32_e32 v78, v142, v78
	v_mul_f32_e32 v79, v79, v208
	v_mul_f32_e32 v79, v143, v79
	global_store_dwordx4 v[62:63], v[76:79], off offset:3072
	s_add_u32 s6, s6, 0x800000
	v_lshl_add_u64 v[62:63], v[6:7], 0, s[6:7]
	v_mul_f32_e32 v80, v80, v209
	v_mul_f32_e32 v80, v128, v80
	v_mul_f32_e32 v81, v81, v209
	v_mul_f32_e32 v81, v129, v81
	v_mul_f32_e32 v82, v82, v209
	v_mul_f32_e32 v82, v130, v82
	v_mul_f32_e32 v83, v83, v209
	v_mul_f32_e32 v83, v131, v83
	global_store_dwordx4 v[62:63], v[80:83], off
	v_mul_f32_e32 v84, v84, v209
	v_mul_f32_e32 v84, v132, v84
	v_mul_f32_e32 v85, v85, v209
	v_mul_f32_e32 v85, v133, v85
	v_mul_f32_e32 v86, v86, v209
	v_mul_f32_e32 v86, v134, v86
	v_mul_f32_e32 v87, v87, v209
	v_mul_f32_e32 v87, v135, v87
	global_store_dwordx4 v[62:63], v[84:87], off offset:1024
	v_mul_f32_e32 v88, v88, v209
	v_mul_f32_e32 v88, v136, v88
	v_mul_f32_e32 v89, v89, v209
	v_mul_f32_e32 v89, v137, v89
	v_mul_f32_e32 v90, v90, v209
	v_mul_f32_e32 v90, v138, v90
	v_mul_f32_e32 v91, v91, v209
	v_mul_f32_e32 v91, v139, v91
	global_store_dwordx4 v[62:63], v[88:91], off offset:2048
	v_mul_f32_e32 v92, v92, v209
	v_mul_f32_e32 v92, v140, v92
	v_mul_f32_e32 v93, v93, v209
	v_mul_f32_e32 v93, v141, v93
	v_mul_f32_e32 v94, v94, v209
	v_mul_f32_e32 v94, v142, v94
	v_mul_f32_e32 v95, v95, v209
	v_mul_f32_e32 v95, v143, v95
	global_store_dwordx4 v[62:63], v[92:95], off offset:3072
	s_add_u32 s6, s6, 0x800000
	v_lshl_add_u64 v[62:63], v[6:7], 0, s[6:7]
	v_mul_f32_e32 v96, v96, v210
	v_mul_f32_e32 v96, v128, v96
	v_mul_f32_e32 v97, v97, v210
	v_mul_f32_e32 v97, v129, v97
	v_mul_f32_e32 v98, v98, v210
	v_mul_f32_e32 v98, v130, v98
	v_mul_f32_e32 v99, v99, v210
	v_mul_f32_e32 v99, v131, v99
	global_store_dwordx4 v[62:63], v[96:99], off
	v_mul_f32_e32 v100, v100, v210
	v_mul_f32_e32 v100, v132, v100
	v_mul_f32_e32 v101, v101, v210
	v_mul_f32_e32 v101, v133, v101
	v_mul_f32_e32 v102, v102, v210
	v_mul_f32_e32 v102, v134, v102
	v_mul_f32_e32 v103, v103, v210
	v_mul_f32_e32 v103, v135, v103
	global_store_dwordx4 v[62:63], v[100:103], off offset:1024
	v_mul_f32_e32 v104, v104, v210
	v_mul_f32_e32 v104, v136, v104
	v_mul_f32_e32 v105, v105, v210
	v_mul_f32_e32 v105, v137, v105
	v_mul_f32_e32 v106, v106, v210
	v_mul_f32_e32 v106, v138, v106
	v_mul_f32_e32 v107, v107, v210
	v_mul_f32_e32 v107, v139, v107
	global_store_dwordx4 v[62:63], v[104:107], off offset:2048
	v_mul_f32_e32 v108, v108, v210
	v_mul_f32_e32 v108, v140, v108
	v_mul_f32_e32 v109, v109, v210
	v_mul_f32_e32 v109, v141, v109
	v_mul_f32_e32 v110, v110, v210
	v_mul_f32_e32 v110, v142, v110
	v_mul_f32_e32 v111, v111, v210
	v_mul_f32_e32 v111, v143, v111
	global_store_dwordx4 v[62:63], v[108:111], off offset:3072
	s_add_u32 s6, s6, 0x800000
	v_lshl_add_u64 v[62:63], v[6:7], 0, s[6:7]
	v_mul_f32_e32 v112, v112, v211
	v_mul_f32_e32 v112, v128, v112
	v_mul_f32_e32 v113, v113, v211
	v_mul_f32_e32 v113, v129, v113
	v_mul_f32_e32 v114, v114, v211
	v_mul_f32_e32 v114, v130, v114
	v_mul_f32_e32 v115, v115, v211
	v_mul_f32_e32 v115, v131, v115
	global_store_dwordx4 v[62:63], v[112:115], off
	v_mul_f32_e32 v116, v116, v211
	v_mul_f32_e32 v116, v132, v116
	v_mul_f32_e32 v117, v117, v211
	v_mul_f32_e32 v117, v133, v117
	v_mul_f32_e32 v118, v118, v211
	v_mul_f32_e32 v118, v134, v118
	v_mul_f32_e32 v119, v119, v211
	v_mul_f32_e32 v119, v135, v119
	global_store_dwordx4 v[62:63], v[116:119], off offset:1024
	v_mul_f32_e32 v120, v120, v211
	v_mul_f32_e32 v120, v136, v120
	v_mul_f32_e32 v121, v121, v211
	v_mul_f32_e32 v121, v137, v121
	v_mul_f32_e32 v122, v122, v211
	v_mul_f32_e32 v122, v138, v122
	v_mul_f32_e32 v123, v123, v211
	v_mul_f32_e32 v123, v139, v123
	global_store_dwordx4 v[62:63], v[120:123], off offset:2048
	v_mul_f32_e32 v124, v124, v211
	v_mul_f32_e32 v124, v140, v124
	v_mul_f32_e32 v125, v125, v211
	v_mul_f32_e32 v125, v141, v125
	v_mul_f32_e32 v126, v126, v211
	v_mul_f32_e32 v126, v142, v126
	v_mul_f32_e32 v127, v127, v211
	v_mul_f32_e32 v127, v143, v127
	global_store_dwordx4 v[62:63], v[124:127], off offset:3072
	s_branch .LBB0_2321
